# code placement test: whole instruction stream shifted by 4 bytes (one s_nop at entry)
# speedup vs baseline: 1.0048x; 1.0048x over previous
_Z4megaILi0ELi10EEv6Params:
	s_nop 0
	s_load_dwordx2 s[48:49], s[0:1], 0xa8
	s_add_u32 s10, s0, 0xa8
	s_addc_u32 s11, s1, 0
	s_mov_b32 s20, s2
	s_mov_b32 s97, s2
	s_waitcnt lgkmcnt(0)
	s_and_b32 s4, s48, 7
	s_cmp_eq_u32 s4, 0
	s_cselect_b64 s[50:51], -1, 0
	s_cmp_lg_u32 s4, 0
	s_cbranch_scc1 .LBB0_2
	s_and_b32 s4, s20, 7
	s_ashr_i32 s5, s48, 3
	s_mul_i32 s4, s5, s4
	s_ashr_i32 s5, s20, 3
	s_add_i32 s97, s4, s5
